# cvhost pre-barrier: LDS transpose round trip overlapped with the item setup / address prep, stores issued last; strict waits
# speedup vs baseline: 1.0018x; 1.0008x over previous
; #define GAS __attribute__((address_space(1)))
; __device__ __forceinline__ unsigned cvt_pk_bf16(float lo, float hi) { unsigned r; asm volatile("v_cvt_pk_bf16_f32 %0, %1, %2" : "=v"(r) : "v"(lo), "v"(hi)); return r; }
; template <class F>
; __device__ __forceinline__ void p0_item_fast(const float* W, int Nsrc, bf16_t* WT, int ldt, const float* ks, float gs, LAS float*  , int kb, int nb, int lane, F srccol) {
;     ...
;     bf16_t* dst = WT + (size_t)(n0 + n4) * ldt + k0 + 8 * kk;
; #pragma unroll
;     for (int e = 0; e < 4; ++e) { u32x4 o; o.x = cvt_pk_bf16(v[0][e], v[1][e]); o.y = cvt_pk_bf16(v[2][e], v[3][e]); o.z = cvt_pk_bf16(v[4][e], v[5][e]); o.w = cvt_pk_bf16(v[6][e], v[7][e]);
;         *(GAS u32x4*)(dst + (size_t)e * ldt) = o; }
.Lcv_nomul:
	v_readfirstlane_b32 s98, v0
	v_and_b32_e32 v76, 63, v0
	v_lshrrev_b32_e32 v77, 2, v76
	v_and_b32_e32 v78, 3, v76
	s_lshr_b32 s98, s98, 6
	s_lshl_b32 s99, s98, 10
	s_cmp_lt_u32 s98, 6
	s_mov_b32 s98, 0x24c00
	s_cselect_b32 s98, 0x1e800, s98
	s_add_i32 s98, s98, s99
	v_lshlrev_b32_e32 v81, 8, v78
	v_lshl_add_u32 v81, v77, 2, v81
	v_add_u32_e32 v81, s98, v81
	v_lshl_add_u32 v82, v76, 4, s98
	v_lshlrev_b32_e32 v83, 3, v78
	v_mad_u32_u24 v83, v77, s91, v83
	ds_write_b32 v81, v238
	ds_write_b32 v81, v239 offset:64
	ds_write_b32 v81, v240 offset:128
	ds_write_b32 v81, v241 offset:192
	ds_read_b128 v[100:103], v82
	ds_write_b32 v81, v242
	ds_write_b32 v81, v243 offset:64
	ds_write_b32 v81, v244 offset:128
	ds_write_b32 v81, v245 offset:192
	ds_read_b128 v[104:107], v82
	s_lshl_b32 s98, s91, 4
	s_mov_b64 s[72:73], s[92:93]
	s_add_u32 s74, s92, s98
	s_addc_u32 s75, s93, 0
	s_add_u32 s92, s92, 32
	s_addc_u32 s93, s93, 0

; #define GAS __attribute__((address_space(1)))
; __device__ __forceinline__ unsigned cvt_pk_bf16(float lo, float hi) { unsigned r; asm volatile("v_cvt_pk_bf16_f32 %0, %1, %2" : "=v"(r) : "v"(lo), "v"(hi)); return r; }
; template <class F>
; __device__ __forceinline__ void p0_item_fast(const float* W, int Nsrc, bf16_t* WT, int ldt, const float* ks, float gs, LAS float*  , int kb, int nb, int lane, F srccol) {
;     ...
;     bf16_t* dst = WT + (size_t)(n0 + n4) * ldt + k0 + 8 * kk;
; #pragma unroll
;     for (int e = 0; e < 4; ++e) { u32x4 o; o.x = cvt_pk_bf16(v[0][e], v[1][e]); o.y = cvt_pk_bf16(v[2][e], v[3][e]); o.z = cvt_pk_bf16(v[4][e], v[5][e]); o.w = cvt_pk_bf16(v[6][e], v[7][e]);
;         *(GAS u32x4*)(dst + (size_t)e * ldt) = o; }
.Lcv_prepdone:
	s_add_i32 s98, s87, -1
	s_cmp_gt_u32 s98, 19
	s_cbranch_scc1 .Lcv_nostore
	s_waitcnt lgkmcnt(0)
	v_cvt_pk_bf16_f32 v100, v100, v101
	v_cvt_pk_bf16_f32 v101, v102, v103
	v_cvt_pk_bf16_f32 v104, v104, v105
	v_cvt_pk_bf16_f32 v105, v106, v107
	global_store_dwordx2 v83, v[100:101], s[72:73]
	global_store_dwordx2 v83, v[104:105], s[74:75]
